# W_in 4th half-round overlapped with LRU/attention mixers (extra barrier before conv, attention items re-dealt 1/3), on top of fused-epilogue load hoist
# speedup vs baseline: 1.0103x; 1.0017x over previous
.LBB0_252:
	s_mov_b64 s[14:15], 0x80
	s_add_i32 m0, s31, 0x18000
	v_lshl_add_u64 v[6:7], v[6:7], 0, s[14:15]
	s_waitcnt vmcnt(2)
	s_barrier
	global_load_lds_dwordx4 v[6:7], off
	v_lshl_add_u64 v[6:7], v[8:9], 0, s[14:15]
	s_add_i32 m0, s31, 0x1a000
	s_add_i32 s37, s31, 0x8000
	global_load_lds_dwordx4 v[6:7], off
	v_lshl_add_u64 v[6:7], v[10:11], 0, s[14:15]
	s_mov_b32 m0, s37
	s_add_i32 s38, s31, 0xa000
	global_load_lds_dwordx4 v[6:7], off
	v_lshl_add_u64 v[6:7], v[12:13], 0, s[14:15]
	s_mov_b32 m0, s38
	s_mov_b64 s[16:17], 0x40080
	global_load_lds_dwordx4 v[6:7], off
	v_lshl_add_u64 v[6:7], v[2:3], 0, s[16:17]
	s_add_i32 m0, s31, 0x1c000
	v_lshl_add_u64 v[8:9], v[6:7], 0, v[134:135]
	global_load_lds_dwordx4 v[8:9], off
	v_lshl_add_u64 v[6:7], v[6:7], 0, v[140:141]
	s_add_i32 m0, s31, 0x1e000
	s_and_b32 s18, s2, 7
	s_lshl_b32 s18, s18, 23
	s_add_u32 s18, s18, 0xd000000
	s_mov_b32 s19, 0
	global_load_lds_dwordx4 v[6:7], off
	v_lshl_add_u64 v[142:143], v[4:5], 0, s[18:19]
	v_lshrrev_b32_e32 v5, 1, v14
	v_and_b32_e32 v5, 24, v5
	v_and_b32_e32 v4, 15, v14
	v_lshlrev_b32_e32 v6, 1, v5
	v_lshl_or_b32 v166, s9, 6, v4
	v_lshl_or_b32 v4, v4, 6, v6
	v_lshlrev_b32_e32 v6, 2, v14
	s_sext_i32_i8 s54, s7
	s_lshl_b32 s7, s9, 13
	v_and_b32_e32 v6, 32, v6
	v_bitop3_b32 v7, v4, s7, v6 bitop3:0xde
	s_lshl_b32 s7, s8, 5
	s_and_b32 s7, s7, 0x60
	s_lshl_b32 s8, s7, 7
	v_bitop3_b32 v167, v4, s8, v6 bitop3:0xde
	v_lshlrev_b32_e32 v4, 14, v18
	v_and_b32_e32 v4, 0xffff8000, v4
	v_or_b32_e32 v169, s7, v5
	v_lshl_add_u32 v4, v19, 11, v4
	v_and_b32_e32 v5, 1, v18
	v_lshl_or_b32 v4, v5, 6, v4
	v_lshl_add_u32 v144, v20, 1, v4
	v_lshlrev_b32_e32 v4, 14, v15
	v_and_b32_e32 v4, 0xffff8000, v4
	s_waitcnt vmcnt(6)
	s_cmpk_lt_u32 s6, 0x100
	v_lshl_add_u32 v4, v16, 11, v4
	v_and_b32_e32 v5, 1, v15
	s_cselect_b64 s[18:19], -1, 0
	s_add_i32 s6, 0, 0x21c00
	v_lshl_or_b32 v4, v5, 6, v4
	s_mov_b32 s22, 0xfffc0080
	s_mov_b32 s55, 0
	v_lshl_add_u32 v168, v166, 4, s6
	v_mov_b32_e32 v145, v135
	v_lshl_add_u32 v146, v17, 1, v4
	v_mov_b32_e32 v147, v135
	v_mov_b64_e32 v[148:149], 0x300
	v_mov_b64_e32 v[150:151], 0x2ff
	s_movk_i32 s39, 0x71
	s_mov_b64 s[20:21], 0x100
	s_mov_b32 s23, -1
	s_add_i32 s42, 0, 0x10000
	s_add_i32 s43, 0, 0x14000
	v_add_u32_e32 v170, 0, v7
	s_add_i32 s44, s31, 0xc000
	s_add_i32 s45, s31, 0xe000
	s_movk_i32 s50, 0xe00
	v_mov_b32_e32 v171, 0x358637bd
	s_mov_b32 s51, 0x800000
	s_mov_b32 s52, 0
	s_barrier
	s_branch .LBB0_255

.Lrm_done_lru_9673:
	s_mov_b32 s10, s68
	s_waitcnt lgkmcnt(0)
	s_barrier
	v_writelane_b32 v255, s3, 0
	v_writelane_b32 v255, s10, 1
	v_writelane_b32 v255, s11, 2
	v_writelane_b32 v255, s12, 3
	v_writelane_b32 v255, s13, 4
	v_writelane_b32 v255, s14, 5
	v_writelane_b32 v255, s15, 6
	v_writelane_b32 v255, s16, 7
	v_writelane_b32 v255, s17, 8
	v_writelane_b32 v255, s20, 9
	v_writelane_b32 v255, s21, 10
	v_writelane_b32 v255, s28, 11
	v_writelane_b32 v255, s30, 12
	v_writelane_b32 v255, s34, 13
	v_writelane_b32 v255, s38, 14
	v_writelane_b32 v255, s48, 15
	v_writelane_b32 v255, s49, 16
	v_writelane_b32 v255, s52, 17
	v_writelane_b32 v255, s53, 18
	v_writelane_b32 v255, s54, 19
	v_writelane_b32 v255, s56, 20
	v_writelane_b32 v255, s57, 21
	v_writelane_b32 v255, s69, 22
	s_add_i32 s2, s2, 0x300
	s_mov_b64 s[6:7], s[0:1]
	s_cmpk_lt_i32 s2, 0x380
	s_waitcnt vmcnt(0)
	v_mov_b64_e32 v[0:1], s[6:7]
	flat_load_dwordx2 v[4:5], v[0:1] offset:216
	s_cselect_b64 s[48:49], -1, 0
	s_ashr_i32 s69, s68, 31
	v_mov_b32_e32 v14, v176
	s_cmpk_gt_i32 s2, 0x37f
	s_nop 0
	v_readfirstlane_b32 s6, v14
	s_cbranch_scc1 .Lwb0_after
	s_lshr_b32 s3, s33, 29
	s_add_i32 s3, s2, s3
	s_ashr_i32 s7, s3, 3
	s_and_b32 s3, s3, -8
	s_sub_i32 s3, s2, s3
	s_cmp_lt_i32 s3, 0
	s_movk_i32 s10, 0x71
	s_cselect_b32 s10, s10, 0x70
	s_mul_i32 s3, s10, s3
	s_add_i32 s3, s3, s7
	s_mul_hi_i32 s7, s3, 0x92492493
	s_add_i32 s7, s7, s3
	s_lshr_b32 s10, s7, 31
	s_ashr_i32 s7, s7, 5
	s_add_i32 s7, s7, s10
	s_lshl_b32 s10, s7, 3
	s_mul_i32 s7, s7, 56
	s_sub_i32 s3, s3, s7
	s_bfe_i32 s7, s3, 0x80000
	s_bfe_u32 s7, s7, 0x3000c
	s_add_i32 s11, s3, s7
	s_bfe_i32 s7, s11, 0x80000
	s_and_b32 s11, s11, 0xf8
	s_sub_i32 s3, s3, s11
	s_sext_i32_i8 s3, s3
	s_sext_i32_i16 s7, s7
	s_add_i32 s30, s10, s3
	s_mov_b64 s[8:9], 0x1a100000
	s_lshr_b32 s7, s7, 3
	s_ashr_i32 s31, s30, 31
	v_readfirstlane_b32 s3, v176
	s_cmpk_gt_u32 s3, 0xff
	s_waitcnt vmcnt(0) lgkmcnt(0)
	v_lshl_add_u64 v[128:129], v[4:5], 0, s[8:9]
	s_cbranch_scc1 .Lwb0_BB0_250
	s_lshl_b64 s[8:9], s[30:31], 8
	s_and_b32 s10, s3, 0xc0
	s_lshl_b32 s3, s3, 4
	s_or_b32 s8, s8, s10
	s_and_b32 s3, s3, 0xc00
	v_mov_b32_e32 v1, s9
	v_or_b32_e32 v0, s8, v177
	s_add_i32 s3, s3, 0
	v_lshl_add_u64 v[0:1], v[0:1], 4, v[128:129]
	s_add_i32 m0, s3, 0x21c00
	s_nop 0
	global_load_lds_dwordx4 v[0:1], off

.Lwb0_after:
	s_sub_i32 s2, s2, 0x300
	v_readlane_b32 s3, v255, 0
	v_readlane_b32 s10, v255, 1
	v_readlane_b32 s11, v255, 2
	v_readlane_b32 s12, v255, 3
	v_readlane_b32 s13, v255, 4
	v_readlane_b32 s14, v255, 5
	v_readlane_b32 s15, v255, 6
	v_readlane_b32 s16, v255, 7
	v_readlane_b32 s17, v255, 8
	v_readlane_b32 s20, v255, 9
	v_readlane_b32 s21, v255, 10
	v_readlane_b32 s28, v255, 11
	v_readlane_b32 s30, v255, 12
	v_readlane_b32 s34, v255, 13
	v_readlane_b32 s38, v255, 14
	v_readlane_b32 s48, v255, 15
	v_readlane_b32 s49, v255, 16
	v_readlane_b32 s52, v255, 17
	v_readlane_b32 s53, v255, 18
	v_readlane_b32 s54, v255, 19
	v_readlane_b32 s56, v255, 20
	v_readlane_b32 s57, v255, 21
	v_readlane_b32 s69, v255, 22
	v_mov_b32_e32 v0, v176
	s_lshl_b32 s3, s3, 3
	v_readfirstlane_b32 s6, v0
	s_ashr_i32 s7, s6, 6
	s_add_i32 s3, s3, s7
	s_mov_b64 s[8:9], s[0:1]
	s_cmpk_gt_i32 s3, 0x7ff
	s_cbranch_scc1 .LBB0_321
	v_bfe_u32 v3, v0, 4, 2
	s_mulk_i32 s7, 0x4400
	v_lshlrev_b32_e32 v77, 2, v3
	v_and_b32_e32 v1, 63, v0
	s_add_i32 s7, s7, 0
	v_and_b32_e32 v72, 15, v0
	v_and_b32_e32 v0, 48, v0
	v_or_b32_e32 v102, 1, v77
	v_or_b32_e32 v104, 2, v77
	v_or_b32_e32 v106, 3, v77
	v_lshlrev_b32_e32 v2, 9, v3
	v_add_u32_e32 v76, s7, v0
	v_lshl_add_u32 v0, v3, 11, s7
	v_lshlrev_b32_e32 v3, 3, v72
	v_lshl_add_u32 v4, v102, 9, s7
	v_lshl_add_u32 v5, v104, 9, s7
	v_lshl_add_u32 v6, v106, 9, s7
	v_add_u32_e32 v79, v0, v3
	v_add_u32_e32 v103, v4, v3
	v_add_u32_e32 v105, v5, v3
	v_add_u32_e32 v107, v6, v3
	v_or_b32_e32 v7, 0x80, v3
	v_or_b32_e32 v3, 0x100, v3
	s_bfe_u32 s6, s6, 0x20006
	s_lshl_b32 s20, s10, 3
	v_add_u32_e32 v112, v0, v3
	v_add_u32_e32 v113, v4, v3
	v_add_u32_e32 v114, v5, v3
	v_add_u32_e32 v115, v6, v3
	v_or_b32_e32 v3, 48, v1
	s_lshl_b32 s10, s6, 6
	v_lshl_add_u32 v73, v1, 1, s7
	v_add_u32_e32 v108, v0, v7
	v_add_u32_e32 v109, v4, v7
	v_add_u32_e32 v110, v5, v7
	v_add_u32_e32 v111, v6, v7
	v_lshlrev_b32_e32 v7, 3, v3
	v_or_b32_e32 v78, s10, v1
	v_lshl_add_u32 v1, v1, 3, s7
	v_mov_b32_e32 v75, 0
	v_add_u32_e32 v116, v0, v7
	s_lshl_b32 s6, s6, 12
	v_or_b32_e32 v0, s10, v72
	v_add_u32_e32 v122, 0x2400, v1
	v_mov_b32_e32 v1, 0x18000800
	s_mov_b32 s11, 0
	v_add_u32_e32 v117, v4, v7
	v_add_u32_e32 v118, v5, v7
	v_add_u32_e32 v119, v6, v7
	v_lshl_add_u32 v120, v72, 1, s7
	v_lshl_add_u32 v121, v3, 1, s7
	v_lshlrev_b32_e32 v80, 3, v78
	v_mov_b32_e32 v81, v75
	v_lshl_or_b32 v82, v78, 2, v1
	v_mov_b32_e32 v83, v75
	v_mov_b64_e32 v[84:85], s[8:9]
	v_lshlrev_b32_e32 v86, 2, v78
	v_mov_b32_e32 v87, v75
	s_and_b32 s12, s2, 7
	s_lshl_b32 s12, s12, 23
	s_add_u32 s12, s12, 0xd000000
	s_mov_b32 s13, 0
	s_lshl_b32 s10, s6, 2
	v_lshlrev_b32_e32 v88, 2, v2
	v_lshlrev_b32_e32 v90, 2, v72
	s_movk_i32 s21, 0x2000
	s_movk_i32 s22, 0x1000
	s_movk_i32 s23, 0x3000
	s_movk_i32 s26, 0x4000
	s_movk_i32 s27, 0x5000
	s_movk_i32 s28, 0x6000
	s_movk_i32 s29, 0x7000
	s_mov_b32 s30, 0x8000
	s_mov_b32 s31, 0x9000
	s_mov_b32 s34, 0xa000
	s_mov_b32 s35, 0xb000
	s_mov_b32 s36, 0xc000
	s_mov_b32 s37, 0xd000
	s_mov_b32 s38, 0xe000
	s_mov_b32 s39, 0xf000
	s_mov_b32 s42, 0x10000
	s_mov_b32 s43, 0x11000
	s_mov_b32 s44, 0x12000
	s_mov_b32 s45, 0x13000
	s_mov_b32 s50, 0x14000
	s_mov_b32 s51, 0x15000
	s_mov_b32 s52, 0x16000
	s_mov_b32 s53, 0x17000
	s_mov_b32 s54, 0x18000
	s_mov_b32 s55, 0x19000
	s_mov_b32 s56, 0x1a000
	s_mov_b32 s57, 0x1b000
	s_mov_b32 s58, 0x1c000
	s_mov_b32 s59, 0x1d000
	s_mov_b32 s60, 0x1e000
	s_mov_b32 s61, 0x1f000
	s_mov_b32 s62, 0x20000
	s_mov_b32 s63, 0x21000
	s_mov_b32 s64, 0x22000
	s_mov_b32 s65, 0x23000
	s_mov_b32 s66, 0x24000
	s_mov_b32 s67, 0x25000
	s_mov_b32 s70, 0x26000
	s_mov_b32 s71, 0x27000
	s_mov_b32 s72, 0x28000
	s_mov_b32 s73, 0x29000
	s_mov_b32 s74, 0x2a000
	s_mov_b32 s75, 0x2b000
	s_mov_b32 s76, 0x2c000
	s_mov_b32 s77, 0x2d000
	s_mov_b32 s78, 0x2e000
	s_mov_b32 s79, 0x2f000
	s_mov_b32 s80, 0x30000
	s_mov_b32 s81, 0x31000
	s_mov_b32 s82, 0x32000
	s_mov_b32 s83, 0x33000
	s_mov_b32 s84, 0x34000
	s_mov_b32 s85, 0x35000
	s_mov_b32 s86, 0x36000
	s_mov_b32 s87, 0x37000
	v_lshlrev_b32_e32 v92, 2, v0
	s_mov_b32 s88, 0x3f2aaaab
	v_mov_b32_e32 v123, 0x3ecc95a3
	s_mov_b32 s89, 0x3f317218
	s_mov_b32 s90, 0x7f800000
	s_mov_b32 s91, 0x33800000
	s_movk_i32 s92, 0x90
	s_mov_b32 s93, 0xf800000
	v_mov_b32_e32 v124, 0x260
	s_mov_b64 s[14:15], 0x1000
	s_mov_b64 s[16:17], 0x4000
	v_mov_b32_e32 v125, 0xe00
	v_mov_b32_e32 v126, 0x7f800000
	v_mov_b32_e32 v127, 0x7fc00000
	v_mov_b32_e32 v128, 0xff800000

.LBB0_321:
	v_mov_b32_e32 v0, v176
	s_cmp_eq_u32 s68, 0x100
	s_cbranch_scc0 .Lrm_orig_attn_12323
	s_and_b32 s3, s2, 7
	s_lshl_b32 s3, s3, 6
	s_lshr_b32 s98, s2, 3
	s_cmp_lt_u32 s98, 16
	s_cbranch_scc1 .Lat_low_attn_12323
	s_mul_i32 s98, s98, 3
	s_sub_i32 s98, s98, 32
	s_add_i32 s3, s3, s98
	s_add_i32 s99, s3, 2
	s_branch .Lat_done_attn_12323
.Lat_low_attn_12323:
	s_add_i32 s3, s3, s98
	s_mov_b32 s99, s3
.Lat_done_attn_12323:
	s_mov_b32 s42, 1
	s_branch .Lrm_done_attn_12323

.LBB0_334:
	v_writelane_b32 v255, s11, 0
	v_writelane_b32 v255, s12, 1
	v_writelane_b32 v255, s13, 2
	v_writelane_b32 v255, s14, 3
	v_writelane_b32 v255, s15, 4
	v_writelane_b32 v255, s16, 5
	v_writelane_b32 v255, s17, 6
	v_writelane_b32 v255, s20, 7
	v_writelane_b32 v255, s21, 8
	v_writelane_b32 v255, s22, 9
	v_writelane_b32 v255, s23, 10
	v_writelane_b32 v255, s28, 11
	v_writelane_b32 v255, s30, 12
	v_writelane_b32 v255, s34, 13
	v_writelane_b32 v255, s38, 14
	s_mov_b64 s[6:7], s[0:1]
	s_waitcnt lgkmcnt(0)
	s_barrier
	s_nop 0
	v_mov_b64_e32 v[0:1], s[6:7]
	flat_load_dwordx2 v[0:1], v[0:1] offset:216
	s_getreg_b32 s3, hwreg(HW_REG_XCC_ID, 0, 4)
	s_waitcnt vmcnt(0)
	s_waitcnt lgkmcnt(0)
	s_barrier
	s_and_saveexec_b64 s[50:51], s[24:25]
	s_cbranch_execz .Lb20_BB0_411
	s_add_i32 s6, 0, 0x23ff0
	v_mov_b32_e32 v2, s6
	s_waitcnt vmcnt(0) expcnt(0) lgkmcnt(0)
	ds_read_b32 v6, v2
	s_add_i32 s6, 0, 0x23ff4
	v_mov_b32_e32 v2, s6
	ds_read_b32 v4, v2
	s_and_b32 s3, s3, 15
	s_waitcnt lgkmcnt(1)
	v_cmp_ne_u32_e32 vcc, 0, v6
	s_cbranch_vccnz .Lb20_BB0_382
	v_readlane_b32 s6, v254, 0
	v_readlane_b32 s7, v254, 1
	s_load_dword s8, s[6:7], 0x14
	s_mov_b64 s[6:7], 0x1000
	v_lshl_add_u64 v[2:3], v[0:1], 0, s[6:7]
	s_mov_b64 s[6:7], 0x1100
	s_waitcnt lgkmcnt(0)
	v_lshl_add_u64 v[4:5], v[0:1], 0, s[6:7]
	s_lshr_b32 s10, s8, 16
	s_and_b32 s8, s8, 0xffff
	s_cmp_lg_u32 s8, 0
	s_cselect_b64 s[8:9], -1, 0
	s_cmp_lg_u64 s[8:9], 0
	s_addc_u32 s8, s87, 0
	s_cmp_lg_u32 s10, 0
	s_mul_i32 s26, s8, s68
	s_cselect_b64 s[8:9], -1, 0
	s_cmp_lg_u64 s[8:9], 0
	s_load_dword s8, s[0:1], 0xe8
	s_mov_b64 s[6:7], 0x1200
	v_lshl_add_u64 v[6:7], v[0:1], 0, s[6:7]
	s_mov_b64 s[6:7], 0x1300
	v_lshl_add_u64 v[8:9], v[0:1], 0, s[6:7]
	s_waitcnt lgkmcnt(0)
	s_addc_u32 s8, s8, 0
	s_mul_i32 s26, s26, s8
	s_mov_b32 s27, 1
	s_mov_b64 s[6:7], 0
	s_branch .Lb20_BB0_372

.Lb20_rm_done_mix2_14932:
	s_waitcnt lgkmcnt(0)
	s_barrier
	v_readlane_b32 s11, v255, 0
	v_readlane_b32 s12, v255, 1
	v_readlane_b32 s13, v255, 2
	v_readlane_b32 s14, v255, 3
	v_readlane_b32 s15, v255, 4
	v_readlane_b32 s16, v255, 5
	v_readlane_b32 s17, v255, 6
	v_readlane_b32 s20, v255, 7
	v_readlane_b32 s21, v255, 8
	v_readlane_b32 s22, v255, 9
	v_readlane_b32 s23, v255, 10
	v_readlane_b32 s28, v255, 11
	v_readlane_b32 s30, v255, 12
	v_readlane_b32 s34, v255, 13
	v_readlane_b32 s38, v255, 14
	v_mov_b32_e32 v54, v176
	s_cmp_eq_u32 s68, 0x100
	s_cbranch_scc0 .Lrm_orig_conf_13188
	s_and_b32 s27, s2, 7
	s_lshl_b32 s27, s27, 7
	s_lshr_b32 s98, s2, 3
	s_add_i32 s27, s27, s98
	s_add_i32 s99, s27, 96
	s_mov_b32 s3, 32
	s_branch .Lrm_done_conf_13188

.LBB0_989:
	s_mov_b64 s[16:17], 0x80
	s_add_i32 m0, s35, 0x18000
	v_lshl_add_u64 v[6:7], v[6:7], 0, s[16:17]
	s_waitcnt vmcnt(2)
	s_barrier
	global_load_lds_dwordx4 v[6:7], off
	v_lshl_add_u64 v[6:7], v[8:9], 0, s[16:17]
	s_add_i32 m0, s35, 0x1a000
	s_add_i32 s39, s35, 0x8000
	global_load_lds_dwordx4 v[6:7], off
	v_lshl_add_u64 v[6:7], v[10:11], 0, s[16:17]
	s_mov_b32 m0, s39
	s_add_i32 s40, s35, 0xa000
	global_load_lds_dwordx4 v[6:7], off
	v_lshl_add_u64 v[6:7], v[12:13], 0, s[16:17]
	s_mov_b32 m0, s40
	s_mov_b64 s[18:19], 0x40080
	global_load_lds_dwordx4 v[6:7], off
	v_lshl_add_u64 v[6:7], v[2:3], 0, s[18:19]
	s_add_i32 m0, s35, 0x1c000
	v_lshl_add_u64 v[8:9], v[6:7], 0, v[134:135]
	global_load_lds_dwordx4 v[8:9], off
	v_lshl_add_u64 v[6:7], v[6:7], 0, v[140:141]
	s_add_i32 m0, s35, 0x1e000
	s_and_b32 s20, s2, 7
	s_lshl_b32 s20, s20, 23
	s_add_u32 s20, s20, 0xd000000
	s_mov_b32 s21, 0
	global_load_lds_dwordx4 v[6:7], off
	v_lshl_add_u64 v[142:143], v[4:5], 0, s[20:21]
	v_lshrrev_b32_e32 v5, 1, v14
	v_and_b32_e32 v5, 24, v5
	v_and_b32_e32 v4, 15, v14
	v_lshlrev_b32_e32 v6, 1, v5
	v_lshl_or_b32 v166, s11, 6, v4
	v_lshl_or_b32 v4, v4, 6, v6
	v_lshlrev_b32_e32 v6, 2, v14
	s_sext_i32_i8 s52, s9
	s_lshl_b32 s9, s11, 13
	v_and_b32_e32 v6, 32, v6
	v_bitop3_b32 v7, v4, s9, v6 bitop3:0xde
	s_lshl_b32 s9, s10, 5
	s_and_b32 s9, s9, 0x60
	s_lshl_b32 s10, s9, 7
	v_bitop3_b32 v167, v4, s10, v6 bitop3:0xde
	v_lshlrev_b32_e32 v4, 14, v18
	v_and_b32_e32 v4, 0xffff8000, v4
	v_or_b32_e32 v169, s9, v5
	v_lshl_add_u32 v4, v19, 11, v4
	v_and_b32_e32 v5, 1, v18
	v_lshl_or_b32 v4, v5, 6, v4
	v_lshl_add_u32 v144, v20, 1, v4
	v_lshlrev_b32_e32 v4, 14, v15
	v_and_b32_e32 v4, 0xffff8000, v4
	s_waitcnt vmcnt(6)
	s_cmpk_lt_u32 s8, 0x100
	v_lshl_add_u32 v4, v16, 11, v4
	v_and_b32_e32 v5, 1, v15
	s_cselect_b64 s[20:21], -1, 0
	s_add_i32 s8, 0, 0x21c00
	v_lshl_or_b32 v4, v5, 6, v4
	s_mov_b32 s26, 0xfffc0080
	s_mov_b32 s53, 0
	v_lshl_add_u32 v168, v166, 4, s8
	v_mov_b32_e32 v145, v135
	v_lshl_add_u32 v146, v17, 1, v4
	v_mov_b32_e32 v147, v135
	v_mov_b64_e32 v[148:149], 0x300
	v_mov_b64_e32 v[150:151], 0x2ff
	s_movk_i32 s41, 0x71
	s_mov_b64 s[22:23], 0x100
	s_mov_b32 s27, -1
	s_add_i32 s42, 0, 0x10000
	s_add_i32 s43, 0, 0x14000
	v_add_u32_e32 v170, 0, v7
	s_add_i32 s44, s35, 0xc000
	s_add_i32 s45, s35, 0xe000
	s_movk_i32 s48, 0xe00
	v_mov_b32_e32 v171, 0x358637bd
	s_mov_b32 s49, 0x800000
	s_mov_b32 s50, 0
	s_barrier
	s_branch .LBB0_992

.Lrm_done_lru_31452:
	s_waitcnt lgkmcnt(0)
	s_barrier
	v_writelane_b32 v255, s3, 0
	v_writelane_b32 v255, s12, 1
	v_writelane_b32 v255, s13, 2
	v_writelane_b32 v255, s14, 3
	v_writelane_b32 v255, s15, 4
	v_writelane_b32 v255, s16, 5
	v_writelane_b32 v255, s17, 6
	v_writelane_b32 v255, s21, 7
	v_writelane_b32 v255, s22, 8
	v_writelane_b32 v255, s23, 9
	v_writelane_b32 v255, s28, 10
	v_writelane_b32 v255, s34, 11
	v_writelane_b32 v255, s50, 12
	s_add_i32 s2, s2, 0x300
	s_mov_b64 s[8:9], s[0:1]
	s_cmpk_lt_i32 s2, 0x380
	s_cselect_b64 s[48:49], -1, 0
	v_mov_b32_e32 v14, v176
	s_waitcnt vmcnt(0)
	v_mov_b64_e32 v[0:1], s[8:9]
	flat_load_dwordx2 v[4:5], v[0:1] offset:216
	s_andn2_b64 vcc, exec, s[48:49]
	v_readfirstlane_b32 s8, v14
	s_cbranch_vccnz .Lwb1_after
	s_lshr_b32 s3, s33, 29
	s_add_i32 s3, s2, s3
	s_ashr_i32 s9, s3, 3
	s_and_b32 s3, s3, -8
	s_sub_i32 s3, s2, s3
	s_cmp_lt_i32 s3, 0
	s_movk_i32 s12, 0x71
	s_cselect_b32 s12, s12, 0x70
	s_mul_i32 s3, s12, s3
	s_add_i32 s3, s3, s9
	s_mul_hi_i32 s9, s3, 0x92492493
	s_add_i32 s9, s9, s3
	s_lshr_b32 s12, s9, 31
	s_ashr_i32 s9, s9, 5
	s_add_i32 s9, s9, s12
	s_lshl_b32 s12, s9, 3
	s_mul_i32 s9, s9, 56
	s_sub_i32 s3, s3, s9
	s_bfe_i32 s9, s3, 0x80000
	s_bfe_u32 s9, s9, 0x3000c
	s_add_i32 s13, s3, s9
	s_bfe_i32 s9, s13, 0x80000
	s_and_b32 s13, s13, 0xf8
	s_sub_i32 s3, s3, s13
	s_sext_i32_i8 s3, s3
	s_sext_i32_i16 s9, s9
	s_add_i32 s34, s12, s3
	s_mov_b64 s[10:11], 0x1a100000
	s_lshr_b32 s9, s9, 3
	s_ashr_i32 s35, s34, 31
	v_readfirstlane_b32 s3, v176
	s_cmpk_gt_u32 s3, 0xff
	s_waitcnt vmcnt(0) lgkmcnt(0)
	v_lshl_add_u64 v[128:129], v[4:5], 0, s[10:11]
	s_cbranch_scc1 .Lwb1_BB0_987
	s_lshl_b64 s[10:11], s[34:35], 8
	s_and_b32 s12, s3, 0xc0
	s_lshl_b32 s3, s3, 4
	s_or_b32 s10, s10, s12
	s_and_b32 s3, s3, 0xc00
	v_mov_b32_e32 v1, s11
	v_or_b32_e32 v0, s10, v177
	s_add_i32 s3, s3, 0
	v_lshl_add_u64 v[0:1], v[0:1], 4, v[128:129]
	s_add_i32 m0, s3, 0x21c00
	s_nop 0
	global_load_lds_dwordx4 v[0:1], off

.Lwb1_after:
	s_sub_i32 s2, s2, 0x300
	v_readlane_b32 s3, v255, 0
	v_readlane_b32 s12, v255, 1
	v_readlane_b32 s13, v255, 2
	v_readlane_b32 s14, v255, 3
	v_readlane_b32 s15, v255, 4
	v_readlane_b32 s16, v255, 5
	v_readlane_b32 s17, v255, 6
	v_readlane_b32 s21, v255, 7
	v_readlane_b32 s22, v255, 8
	v_readlane_b32 s23, v255, 9
	v_readlane_b32 s28, v255, 10
	v_readlane_b32 s34, v255, 11
	v_readlane_b32 s50, v255, 12
	v_mov_b32_e32 v0, v176
	s_lshl_b32 s3, s3, 3
	v_readfirstlane_b32 s8, v0
	s_ashr_i32 s9, s8, 6
	s_add_i32 s3, s3, s9
	s_mov_b64 s[10:11], s[0:1]
	s_cmpk_gt_i32 s3, 0x7ff
	s_cbranch_scc1 .LBB0_1058
	v_bfe_u32 v3, v0, 4, 2
	s_mulk_i32 s9, 0x4400
	v_lshlrev_b32_e32 v77, 2, v3
	v_and_b32_e32 v1, 63, v0
	s_add_i32 s9, s9, 0
	v_and_b32_e32 v72, 15, v0
	v_and_b32_e32 v0, 48, v0
	v_or_b32_e32 v102, 1, v77
	v_or_b32_e32 v104, 2, v77
	v_or_b32_e32 v106, 3, v77
	v_lshlrev_b32_e32 v2, 9, v3
	v_add_u32_e32 v76, s9, v0
	v_lshl_add_u32 v0, v3, 11, s9
	v_lshlrev_b32_e32 v3, 3, v72
	v_lshl_add_u32 v4, v102, 9, s9
	v_lshl_add_u32 v5, v104, 9, s9
	v_lshl_add_u32 v6, v106, 9, s9
	v_add_u32_e32 v79, v0, v3
	v_add_u32_e32 v103, v4, v3
	v_add_u32_e32 v105, v5, v3
	v_add_u32_e32 v107, v6, v3
	v_or_b32_e32 v7, 0x80, v3
	v_or_b32_e32 v3, 0x100, v3
	s_bfe_u32 s8, s8, 0x20006
	s_lshl_b32 s26, s12, 3
	v_add_u32_e32 v112, v0, v3
	v_add_u32_e32 v113, v4, v3
	v_add_u32_e32 v114, v5, v3
	v_add_u32_e32 v115, v6, v3
	v_or_b32_e32 v3, 48, v1
	s_lshl_b32 s12, s8, 6
	v_lshl_add_u32 v73, v1, 1, s9
	v_add_u32_e32 v108, v0, v7
	v_add_u32_e32 v109, v4, v7
	v_add_u32_e32 v110, v5, v7
	v_add_u32_e32 v111, v6, v7
	v_lshlrev_b32_e32 v7, 3, v3
	v_or_b32_e32 v78, s12, v1
	v_lshl_add_u32 v1, v1, 3, s9
	v_mov_b32_e32 v75, 0
	v_add_u32_e32 v116, v0, v7
	s_lshl_b32 s8, s8, 12
	v_or_b32_e32 v0, s12, v72
	v_add_u32_e32 v122, 0x2400, v1
	v_mov_b32_e32 v1, 0x18000800
	s_mov_b32 s13, 0
	v_add_u32_e32 v117, v4, v7
	v_add_u32_e32 v118, v5, v7
	v_add_u32_e32 v119, v6, v7
	v_lshl_add_u32 v120, v72, 1, s9
	v_lshl_add_u32 v121, v3, 1, s9
	v_lshlrev_b32_e32 v80, 3, v78
	v_mov_b32_e32 v81, v75
	v_lshl_or_b32 v82, v78, 2, v1
	v_mov_b32_e32 v83, v75
	v_mov_b64_e32 v[84:85], s[10:11]
	v_lshlrev_b32_e32 v86, 2, v78
	v_mov_b32_e32 v87, v75
	s_mov_b64 s[14:15], 0x1000
	s_movk_i32 s27, 0x1000
	s_and_b32 s16, s2, 7
	s_lshl_b32 s16, s16, 23
	s_add_u32 s16, s16, 0xd000000
	s_mov_b32 s17, 0
	s_lshl_b32 s12, s8, 2
	v_lshlrev_b32_e32 v88, 2, v2
	v_lshlrev_b32_e32 v90, 2, v72
	s_mov_b64 s[18:19], 0x10000
	s_mov_b32 s28, 0x10000
	s_mov_b32 s29, 0x12000
	s_movk_i32 s30, 0x2000
	s_movk_i32 s31, 0x3000
	s_movk_i32 s34, 0x4000
	s_movk_i32 s35, 0x5000
	s_movk_i32 s36, 0x6000
	s_movk_i32 s37, 0x7000
	s_mov_b32 s38, 0x8000
	s_mov_b32 s39, 0x9000
	s_mov_b32 s40, 0xa000
	s_mov_b32 s41, 0xb000
	s_mov_b32 s42, 0xc000
	s_mov_b32 s43, 0xd000
	s_mov_b32 s44, 0xe000
	s_mov_b32 s45, 0xf000
	s_mov_b32 s48, 0x11000
	s_mov_b32 s49, 0x13000
	s_mov_b32 s50, 0x14000
	s_mov_b32 s51, 0x15000
	s_mov_b32 s52, 0x16000
	s_mov_b32 s53, 0x17000
	s_mov_b32 s54, 0x18000
	s_mov_b32 s55, 0x19000
	s_mov_b32 s56, 0x1a000
	s_mov_b32 s57, 0x1b000
	s_mov_b32 s58, 0x1c000
	s_mov_b32 s59, 0x1d000
	s_mov_b32 s60, 0x1e000
	s_mov_b32 s61, 0x1f000
	s_mov_b32 s62, 0x20000
	s_mov_b32 s63, 0x21000
	s_mov_b32 s64, 0x22000
	s_mov_b32 s65, 0x23000
	s_mov_b32 s66, 0x24000
	s_mov_b32 s67, 0x25000
	s_mov_b32 s70, 0x26000
	s_mov_b32 s71, 0x27000
	s_mov_b32 s72, 0x28000
	s_mov_b32 s73, 0x29000
	s_mov_b32 s74, 0x2a000
	s_mov_b32 s75, 0x2b000
	s_mov_b32 s76, 0x2c000
	s_mov_b32 s77, 0x2d000
	s_mov_b32 s78, 0x2e000
	s_mov_b32 s79, 0x2f000
	s_mov_b32 s80, 0x30000
	s_mov_b32 s81, 0x31000
	s_mov_b32 s82, 0x32000
	s_mov_b32 s83, 0x33000
	s_mov_b32 s84, 0x34000
	s_mov_b32 s85, 0x35000
	s_mov_b32 s86, 0x36000
	s_mov_b32 s87, 0x37000
	v_lshlrev_b32_e32 v92, 2, v0
	s_mov_b32 s88, 0x3f2aaaab
	v_mov_b32_e32 v123, 0x3ecc95a3
	s_mov_b32 s89, 0x3f317218
	s_mov_b32 s90, 0x7f800000
	s_mov_b32 s91, 0x33800000
	s_movk_i32 s92, 0x90
	s_mov_b32 s93, 0xf800000
	v_mov_b32_e32 v124, 0x260
	s_mov_b64 s[20:21], 0x4000
	v_mov_b32_e32 v125, 0xe00
	v_mov_b32_e32 v126, 0x7f800000
	v_mov_b32_e32 v127, 0x7fc00000
	v_mov_b32_e32 v128, 0xff800000

.LBB0_1071:
	v_writelane_b32 v255, s11, 0
	v_writelane_b32 v255, s12, 1
	v_writelane_b32 v255, s13, 2
	v_writelane_b32 v255, s14, 3
	v_writelane_b32 v255, s15, 4
	v_writelane_b32 v255, s16, 5
	v_writelane_b32 v255, s17, 6
	v_writelane_b32 v255, s21, 7
	v_writelane_b32 v255, s22, 8
	v_writelane_b32 v255, s23, 9
	v_writelane_b32 v255, s26, 10
	v_writelane_b32 v255, s28, 11
	v_writelane_b32 v255, s34, 12
	s_mov_b64 s[8:9], s[0:1]
	s_waitcnt lgkmcnt(0)
	s_barrier
	s_nop 0
	v_mov_b64_e32 v[0:1], s[8:9]
	flat_load_dwordx2 v[0:1], v[0:1] offset:216
	s_getreg_b32 s3, hwreg(HW_REG_XCC_ID, 0, 4)
	s_waitcnt vmcnt(0)
	s_waitcnt lgkmcnt(0)
	s_barrier
	s_and_saveexec_b64 s[48:49], s[24:25]
	s_cbranch_execz .Lb21_BB0_1148
	s_add_i32 s8, 0, 0x23ff0
	v_mov_b32_e32 v2, s8
	s_waitcnt vmcnt(0) expcnt(0) lgkmcnt(0)
	ds_read_b32 v6, v2
	s_add_i32 s8, 0, 0x23ff4
	v_mov_b32_e32 v2, s8
	ds_read_b32 v4, v2
	s_and_b32 s3, s3, 15
	s_waitcnt lgkmcnt(1)
	v_cmp_ne_u32_e32 vcc, 0, v6
	s_cbranch_vccnz .Lb21_BB0_1119
	v_readlane_b32 s8, v254, 0
	v_readlane_b32 s9, v254, 1
	s_load_dword s10, s[8:9], 0x14
	s_mov_b64 s[8:9], 0x1000
	v_lshl_add_u64 v[2:3], v[0:1], 0, s[8:9]
	s_mov_b64 s[8:9], 0x1100
	s_waitcnt lgkmcnt(0)
	v_lshl_add_u64 v[4:5], v[0:1], 0, s[8:9]
	s_lshr_b32 s12, s10, 16
	s_and_b32 s10, s10, 0xffff
	s_cmp_lg_u32 s10, 0
	s_cselect_b64 s[10:11], -1, 0
	s_cmp_lg_u64 s[10:11], 0
	s_addc_u32 s10, s87, 0
	s_cmp_lg_u32 s12, 0
	s_mul_i32 s28, s10, s68
	s_cselect_b64 s[10:11], -1, 0
	s_cmp_lg_u64 s[10:11], 0
	s_load_dword s10, s[0:1], 0xe8
	s_mov_b64 s[8:9], 0x1200
	v_lshl_add_u64 v[6:7], v[0:1], 0, s[8:9]
	s_mov_b64 s[8:9], 0x1300
	v_lshl_add_u64 v[8:9], v[0:1], 0, s[8:9]
	s_waitcnt lgkmcnt(0)
	s_addc_u32 s10, s10, 0
	s_mul_i32 s28, s28, s10
	s_mov_b32 s29, 1
	s_mov_b64 s[8:9], 0
	s_branch .Lb21_BB0_1109

.Lb21_rm_done_mix2_36721:
	s_waitcnt lgkmcnt(0)
	s_barrier
	v_readlane_b32 s11, v255, 0
	v_readlane_b32 s12, v255, 1
	v_readlane_b32 s13, v255, 2
	v_readlane_b32 s14, v255, 3
	v_readlane_b32 s15, v255, 4
	v_readlane_b32 s16, v255, 5
	v_readlane_b32 s17, v255, 6
	v_readlane_b32 s21, v255, 7
	v_readlane_b32 s22, v255, 8
	v_readlane_b32 s23, v255, 9
	v_readlane_b32 s26, v255, 10
	v_readlane_b32 s28, v255, 11
	v_readlane_b32 s34, v255, 12
	v_mov_b32_e32 v54, v176
	s_cmp_eq_u32 s68, 0x100
	s_cbranch_scc0 .Lrm_orig_conf_34981
	s_and_b32 s29, s2, 7
	s_lshl_b32 s29, s29, 7
	s_lshr_b32 s98, s2, 3
	s_add_i32 s29, s29, s98
	s_add_i32 s99, s29, 96
	s_mov_b32 s3, 32
	s_branch .Lrm_done_conf_34981

	.amdhsa_kernel _Z9hymba_fwd4Args
		.amdhsa_group_segment_fixed_size 0
		.amdhsa_private_segment_fixed_size 0
		.amdhsa_kernarg_size 480
		.amdhsa_user_sgpr_count 2
		.amdhsa_user_sgpr_dispatch_ptr 0
		.amdhsa_user_sgpr_queue_ptr 0
		.amdhsa_user_sgpr_kernarg_segment_ptr 1
		.amdhsa_user_sgpr_dispatch_id 0
		.amdhsa_user_sgpr_kernarg_preload_length 0
		.amdhsa_user_sgpr_kernarg_preload_offset 0
		.amdhsa_user_sgpr_private_segment_size 0
		.amdhsa_uses_dynamic_stack 0
		.amdhsa_enable_private_segment 0
		.amdhsa_system_sgpr_workgroup_id_x 1
		.amdhsa_system_sgpr_workgroup_id_y 0
		.amdhsa_system_sgpr_workgroup_id_z 0
		.amdhsa_system_sgpr_workgroup_info 0
		.amdhsa_system_vgpr_workitem_id 2
		.amdhsa_next_free_vgpr 256
		.amdhsa_next_free_sgpr 102
		.amdhsa_accum_offset 256
		.amdhsa_reserve_vcc 1
		.amdhsa_float_round_mode_32 0
		.amdhsa_float_round_mode_16_64 0
		.amdhsa_float_denorm_mode_32 3
		.amdhsa_float_denorm_mode_16_64 3
		.amdhsa_dx10_clamp 1
		.amdhsa_ieee_mode 1
		.amdhsa_fp16_overflow 0
		.amdhsa_tg_split 0
		.amdhsa_exception_fp_ieee_invalid_op 0
		.amdhsa_exception_fp_denorm_src 0
		.amdhsa_exception_fp_ieee_div_zero 0
		.amdhsa_exception_fp_ieee_overflow 0
		.amdhsa_exception_fp_ieee_underflow 0
		.amdhsa_exception_fp_ieee_inexact 0
		.amdhsa_exception_int_div_zero 0
	.end_amdhsa_kernel

amdhsa.kernels:
  - .agpr_count:     0
    .args:
      - .offset:         0
        .size:           224
        .value_kind:     by_value
      - .offset:         224
        .size:           4
        .value_kind:     hidden_block_count_x
      - .offset:         228
        .size:           4
        .value_kind:     hidden_block_count_y
      - .offset:         232
        .size:           4
        .value_kind:     hidden_block_count_z
      - .offset:         236
        .size:           2
        .value_kind:     hidden_group_size_x
      - .offset:         238
        .size:           2
        .value_kind:     hidden_group_size_y
      - .offset:         240
        .size:           2
        .value_kind:     hidden_group_size_z
      - .offset:         242
        .size:           2
        .value_kind:     hidden_remainder_x
      - .offset:         244
        .size:           2
        .value_kind:     hidden_remainder_y
      - .offset:         246
        .size:           2
        .value_kind:     hidden_remainder_z
      - .offset:         264
        .size:           8
        .value_kind:     hidden_global_offset_x
      - .offset:         272
        .size:           8
        .value_kind:     hidden_global_offset_y
      - .offset:         280
        .size:           8
        .value_kind:     hidden_global_offset_z
      - .offset:         288
        .size:           2
        .value_kind:     hidden_grid_dims
      - .offset:         312
        .size:           8
        .value_kind:     hidden_multigrid_sync_arg
      - .offset:         344
        .size:           4
        .value_kind:     hidden_dynamic_lds_size
    .group_segment_fixed_size: 0
    .kernarg_segment_align: 8
    .kernarg_segment_size: 480
    .language:       OpenCL C
    .language_version:
      - 2
      - 0
    .max_flat_workgroup_size: 512
    .name:           _Z9hymba_fwd4Args
    .private_segment_fixed_size: 0
    .sgpr_count:     108
    .sgpr_spill_count: 2
    .symbol:         _Z9hymba_fwd4Args.kd
    .uniform_work_group_size: 1
    .uses_dynamic_stack: false
    .vgpr_count:     256
    .vgpr_spill_count: 0
    .wavefront_size: 64
